# MoE GEMM setup: the eight per-expert count loads issued together (were load-wait-readfirstlane chains after each grid barrier); gather-index wait at MoE tile start counted (vmcnt 8) instead of full dr
# speedup vs baseline: 1.0046x; 1.0046x over previous
; #define KON(k) if (!((KIND_MASK >> (k)) & 1)) break;
; __global__ void __launch_bounds__(NTHR, 2) mega_fwd(Params P) {
;     ...
;             case K_WOSPLIT: KON(K_WOSPLIT) { SchedSplit S; S.cnt = (const int*)(ws + O_CTL) + a0 * 8 * CSTR; S.moe = a1;
;                 if (a1) { int t = 0;
; #pragma unroll
;                     for (int e = 0; e < NEXP; ++e) t += (S.cnt[e * CSTR] + 255) >> 8;
;                     S.tile0 = 128; S.ntile = t - 128; S.A = (const char*)(ws + O_HIDS); S.B = (const char*)(ws + O_MWO + (size_t)a0 * 8 * 1024 * 3584 * 2); S.estride = (size_t)1024 * 3584 * 2; }
;                 else { S.tile0 = 64; S.ntile = 1; S.A = (const char*)(ws + O_HID); S.B = (const char*)(ws + O_FWO); S.estride = 0; }
;                 EpiPartial E{(float*)(ws + O_YSP)}; gemm_phase(lds, KCH, DFF, DFF, S, E);
.LBB0_183:
	s_xor_b64 s[4:5], s[4:5], -1
	s_lshl_b64 s[0:1], s[6:7], 2
	v_writelane_b32 v253, s12, 48
	s_add_u32 s0, s83, s0
	s_addc_u32 s1, s84, s1
	v_writelane_b32 v253, s13, 49
	v_writelane_b32 v253, s11, 50
	s_add_u32 s92, s0, 0x2000
	v_writelane_b32 v253, s0, 51
	s_addc_u32 s93, s1, 0
	v_writelane_b32 v253, s1, 52
	s_cmp_lt_i32 s47, 10
	s_mov_b64 s[0:1], -1
	s_mov_b32 s94, s47
	s_cbranch_scc1 .LBB0_717
	s_cmp_lt_i32 s47, 14
	s_cbranch_scc1 .LBB0_372
	s_cmp_lt_i32 s47, 16
	s_cbranch_scc1 .LBB0_276
	s_cmp_lt_i32 s47, 17
	s_cbranch_scc1 .LBB0_262
	s_cmp_gt_i32 s47, 17
	s_cbranch_scc0 .LBB0_248
	v_readlane_b32 s0, v252, 30
	v_readlane_b32 s1, v252, 31
	v_readlane_b32 s8, v253, 50
	s_mov_b32 s3, s1
	s_lshl_b32 s2, s8, 9
	v_writelane_b32 v252, s0, 30
	v_cndmask_b32_e64 v0, 0, 1, s[4:5]
	s_nop 0
	v_writelane_b32 v252, s1, 31
	s_lshl_b64 s[0:1], s[2:3], 2
	s_add_u32 s6, s28, s0
	s_addc_u32 s7, s29, s1
	v_cmp_ne_u32_e64 s[0:1], 1, v0
	s_andn2_b64 vcc, exec, s[4:5]
	s_cbranch_vccnz .LBB0_190
	global_load_dword v238, v1, s[6:7]
	global_load_dword v239, v1, s[6:7] offset:256
	global_load_dword v240, v1, s[6:7] offset:512
	global_load_dword v241, v1, s[6:7] offset:768
	global_load_dword v242, v1, s[6:7] offset:1024
	global_load_dword v243, v1, s[6:7] offset:1280
	global_load_dword v244, v1, s[6:7] offset:1536
	global_load_dword v245, v1, s[6:7] offset:1792
	s_waitcnt vmcnt(0)
	v_mov_b32_e32 v0, v238
	s_mov_b64 s[10:11], 0x700000
	v_readlane_b32 s12, v250, 15
	s_movk_i32 s11, 0x80
	v_readlane_b32 s13, v250, 16
	s_waitcnt vmcnt(0)
	v_readfirstlane_b32 s2, v0
	v_mov_b32_e32 v0, v239
	s_addk_i32 s2, 0xff
	s_ashr_i32 s2, s2, 8
	s_waitcnt vmcnt(0)
	v_readfirstlane_b32 s3, v0
	v_mov_b32_e32 v0, v240
	s_addk_i32 s3, 0xff
	s_ashr_i32 s3, s3, 8
	s_add_i32 s3, s3, s2
	s_waitcnt vmcnt(0)
	v_readfirstlane_b32 s2, v0
	v_mov_b32_e32 v0, v241
	s_addk_i32 s2, 0xff
	s_ashr_i32 s2, s2, 8
	s_add_i32 s2, s2, s3
	s_waitcnt vmcnt(0)
	v_readfirstlane_b32 s3, v0
	v_mov_b32_e32 v0, v242
	s_addk_i32 s3, 0xff
	s_ashr_i32 s3, s3, 8
	s_add_i32 s3, s3, s2
	s_waitcnt vmcnt(0)
	v_readfirstlane_b32 s2, v0
	v_mov_b32_e32 v0, v243
	s_addk_i32 s2, 0xff
	s_ashr_i32 s2, s2, 8
	s_add_i32 s2, s2, s3
	s_waitcnt vmcnt(0)
	v_readfirstlane_b32 s3, v0
	v_mov_b32_e32 v0, v244
	s_addk_i32 s3, 0xff
	s_ashr_i32 s3, s3, 8
	s_add_i32 s3, s3, s2
	s_waitcnt vmcnt(0)
	v_readfirstlane_b32 s2, v0
	v_mov_b32_e32 v0, v245
	s_addk_i32 s2, 0xff
	s_ashr_i32 s2, s2, 8
	s_add_i32 s2, s2, s3
	s_waitcnt vmcnt(0)
	v_readfirstlane_b32 s3, v0
	s_addk_i32 s3, 0xff
	s_ashr_i32 s3, s3, 8
	s_add_i32 s2, s3, s2
	s_mul_i32 s3, s8, 0x3800000
	s_add_u32 s8, s52, s3
	s_mul_i32 s2, s2, 28
	s_addc_u32 s9, s53, 0
	s_add_i32 s18, s2, 0xfffff200
	s_branch .LBB0_191

; __device__ __forceinline__ int get_bid() { int b = blockIdx.x; asm volatile("" : "+s"(b)); return b; }
;     __device__ __forceinline__ bool next(int i, Unit& u) const {
;         const int L = i * (int)gridDim.x + get_bid(); if (L >= ntile * 4 * KSPL) return false;
;         const int t = L / (4 * KSPL), rem = L % (4 * KSPL), ks = rem >> 2, pn = rem & 3, pm = tile0 + t;
;         int es = 0;
;         if (moe) { int a2 = 0;
; #pragma unroll
;             for (int e = 0; e < NEXP; ++e) { const int tt = (cnt[e * CSTR] + 255) >> 8; if (pm >= a2 && pm < a2 + tt) es = e; a2 += tt; } }
;         u.pm = t; u.pn = pn * KSPL + ks;
;         u.a = A + ((size_t)pm * 256 * DFF + ks * KCH) * 2; u.b = B + (size_t)es * estride + ((size_t)pn * 256 * DFF + ks * KCH) * 2; return true;
.LBB0_191:
	v_mov_b32_e32 v4, v196
	s_mov_b32 s43, s74
	s_cmp_ge_i32 s43, s18
	v_readfirstlane_b32 s19, v4
	s_cbranch_scc1 .LBB0_207
	s_mul_hi_i32 s2, s43, 0x92492493
	s_add_i32 s2, s2, s43
	s_lshr_b32 s3, s2, 31
	s_ashr_i32 s2, s2, 4
	s_add_i32 s30, s2, s3
	s_add_i32 s42, s30, s11
	s_and_b64 vcc, exec, s[0:1]
	v_mov_b64_e32 v[2:3], 0
	s_cbranch_vccnz .LBB0_194
	global_load_dword v238, v1, s[6:7]
	global_load_dword v239, v1, s[6:7] offset:256
	global_load_dword v240, v1, s[6:7] offset:512
	global_load_dword v241, v1, s[6:7] offset:768
	global_load_dword v242, v1, s[6:7] offset:1024
	global_load_dword v243, v1, s[6:7] offset:1280
	global_load_dword v244, v1, s[6:7] offset:1536
	global_load_dword v245, v1, s[6:7] offset:1792
	s_waitcnt vmcnt(0)
	v_mov_b32_e32 v0, v238
	v_mov_b32_e32 v2, v243
	s_waitcnt vmcnt(0)
	v_readfirstlane_b32 s2, v0
	v_mov_b32_e32 v0, v239
	s_addk_i32 s2, 0xff
	s_ashr_i32 s2, s2, 8
	s_waitcnt vmcnt(1)
	v_add_u32_e32 v2, 0xff, v2
	v_ashrrev_i32_e32 v2, 8, v2
	s_waitcnt vmcnt(0)
	v_readfirstlane_b32 s3, v0
	v_mov_b32_e32 v0, v240
	s_addk_i32 s3, 0xff
	s_ashr_i32 s3, s3, 8
	s_cmp_ge_i32 s42, s2
	s_cselect_b64 s[4:5], -1, 0
	s_add_i32 s3, s3, s2
	s_cmp_lt_i32 s42, s3
	s_cselect_b64 s[14:15], -1, 0
	s_and_b64 s[16:17], s[4:5], s[14:15]
	s_waitcnt vmcnt(0)
	v_readfirstlane_b32 s2, v0
	v_mov_b32_e32 v0, v241
	s_addk_i32 s2, 0xff
	s_ashr_i32 s2, s2, 8
	s_cmp_ge_i32 s42, s3
	s_cselect_b64 s[4:5], -1, 0
	s_add_i32 s2, s2, s3
	s_cmp_lt_i32 s42, s2
	s_cselect_b64 s[14:15], -1, 0
	s_and_b64 s[34:35], s[4:5], s[14:15]
	s_waitcnt vmcnt(0)
	v_readfirstlane_b32 s3, v0
	v_mov_b32_e32 v0, v242
	s_addk_i32 s3, 0xff
	s_ashr_i32 s3, s3, 8
	s_cmp_ge_i32 s42, s2
	s_cselect_b64 s[4:5], -1, 0
	s_add_i32 s3, s3, s2
	s_cmp_lt_i32 s42, s3
	s_cselect_b64 s[14:15], -1, 0
	s_and_b64 s[14:15], s[4:5], s[14:15]
	s_cmp_ge_i32 s42, s3
	s_cselect_b64 s[4:5], -1, 0
	s_waitcnt vmcnt(0)
	v_add_u32_e32 v0, 0xff, v0
	v_ashrrev_i32_e32 v0, 8, v0
	v_add_u32_e32 v0, s3, v0
	v_cmp_lt_i32_e32 vcc, s42, v0
	s_and_b64 s[36:37], s[4:5], vcc
	v_cmp_ge_i32_e32 vcc, s42, v0
	v_add_u32_e32 v0, v2, v0
	v_mov_b32_e32 v2, v244
	v_cmp_lt_i32_e64 s[4:5], s42, v0
	s_and_b64 s[38:39], vcc, s[4:5]
	v_cmp_ge_i32_e32 vcc, s42, v0
	s_waitcnt vmcnt(0)
	v_add_u32_e32 v2, 0xff, v2
	v_ashrrev_i32_e32 v2, 8, v2
	v_add_u32_e32 v0, v2, v0
	v_mov_b32_e32 v2, v245
	v_cmp_lt_i32_e64 s[4:5], s42, v0
	s_and_b64 s[40:41], vcc, s[4:5]
	v_cmp_ge_i32_e32 vcc, s42, v0
	s_waitcnt vmcnt(0)
	v_add_u32_e32 v2, 0xff, v2
	v_ashrrev_i32_e32 v2, 8, v2
	v_add_u32_e32 v0, v2, v0
	v_cmp_lt_i32_e64 s[4:5], s42, v0
	v_cndmask_b32_e64 v0, 0, 1, s[16:17]
	v_cndmask_b32_e64 v0, v0, 2, s[34:35]
	v_cndmask_b32_e64 v0, v0, 3, s[14:15]
	v_cndmask_b32_e64 v0, v0, 4, s[36:37]
	v_cndmask_b32_e64 v0, v0, 5, s[38:39]
	s_and_b64 s[4:5], vcc, s[4:5]
	v_cndmask_b32_e64 v0, v0, 6, s[40:41]
	v_cndmask_b32_e64 v2, v0, 7, s[4:5]

;     __device__ __forceinline__ void init(const int* cnt_, const void* A_, const void* B_, int N, int K, int rowmajor_, int maxT) {
;         rowmajor = rowmajor_;
;         cnt = cnt_; nN = N / BM; A = (const char*)A_; B = (const char*)B_; tstep = (size_t)BM * K * 2; estride = (size_t)N * K * 2;
;         int t = 0;
; #pragma unroll
;         for (int e = 0; e < NEXP; ++e) { tl[e] = __builtin_amdgcn_readfirstlane((cnt[e * CSTR] + 255) >> 8); t += tl[e]; }
;         T = t < maxT ? t : maxT;
;     }
.LBB0_372:
	s_andn2_b64 vcc, exec, s[0:1]
	s_cbranch_vccnz .LBB0_716
	s_cmp_lt_i32 s47, 12
	s_mov_b64 s[0:1], -1
	s_cbranch_scc1 .LBB0_562
	v_readlane_b32 s80, v250, 19
	s_cmp_gt_i32 s47, 12
	v_readlane_b32 s81, v250, 20
	s_cbranch_scc0 .LBB0_399
	v_readlane_b32 s0, v252, 30
	v_readlane_b32 s1, v252, 31
	v_readlane_b32 s0, v253, 50
	s_mov_b32 s3, s1
	s_lshl_b32 s2, s0, 9
	v_writelane_b32 v252, s0, 30
	v_mov_b32_e32 v2, v196
	s_mov_b32 s4, s74
	v_writelane_b32 v252, s1, 31
	s_lshl_b64 s[0:1], s[2:3], 2
	s_add_u32 s0, s28, s0
	s_addc_u32 s1, s29, s1
	global_load_dword v238, v1, s[0:1]
	global_load_dword v239, v1, s[0:1] offset:256
	global_load_dword v240, v1, s[0:1] offset:512
	global_load_dword v241, v1, s[0:1] offset:768
	global_load_dword v242, v1, s[0:1] offset:1024
	global_load_dword v243, v1, s[0:1] offset:1280
	global_load_dword v244, v1, s[0:1] offset:1536
	global_load_dword v245, v1, s[0:1] offset:1792
	s_waitcnt vmcnt(0)
	v_mov_b32_e32 v0, v238
	s_waitcnt vmcnt(0)
	v_readfirstlane_b32 s2, v0
	v_mov_b32_e32 v0, v239
	s_addk_i32 s2, 0xff
	s_ashr_i32 s18, s2, 8
	s_waitcnt vmcnt(0)
	v_readfirstlane_b32 s2, v0
	v_mov_b32_e32 v0, v240
	s_addk_i32 s2, 0xff
	s_ashr_i32 s19, s2, 8
	s_add_i32 s19, s19, s18
	s_waitcnt vmcnt(0)
	v_readfirstlane_b32 s2, v0
	v_mov_b32_e32 v0, v241
	s_addk_i32 s2, 0xff
	s_ashr_i32 s30, s2, 8
	s_add_i32 s30, s30, s19
	s_waitcnt vmcnt(0)
	v_readfirstlane_b32 s2, v0
	v_mov_b32_e32 v0, v242
	s_addk_i32 s2, 0xff
	s_ashr_i32 s34, s2, 8
	s_add_i32 s34, s34, s30
	s_waitcnt vmcnt(0)
	v_readfirstlane_b32 s2, v0
	v_mov_b32_e32 v0, v243
	s_addk_i32 s2, 0xff
	s_ashr_i32 s35, s2, 8
	s_add_i32 s35, s35, s34
	s_waitcnt vmcnt(0)
	v_readfirstlane_b32 s2, v0
	v_mov_b32_e32 v0, v244
	s_addk_i32 s2, 0xff
	s_ashr_i32 s36, s2, 8
	s_add_i32 s36, s36, s35
	s_waitcnt vmcnt(0)
	v_readfirstlane_b32 s2, v0
	v_mov_b32_e32 v0, v245
	s_addk_i32 s2, 0xff
	s_ashr_i32 s37, s2, 8
	s_add_i32 s37, s37, s36
	s_waitcnt vmcnt(0)
	v_readfirstlane_b32 s0, v0
	s_addk_i32 s0, 0xff
	s_ashr_i32 s38, s0, 8
	s_add_i32 s38, s38, s37
	s_min_i32 s0, s38, 0x80
	s_lshl_b32 s40, s0, 2
	v_readfirstlane_b32 s85, v2
	s_cmp_ge_i32 s4, s40
	s_cbranch_scc1 .LBB0_398
	s_ashr_i32 s83, s0, 1
	s_and_b32 s42, s40, 4
	s_and_b32 s5, s4, 7
	s_add_i32 s84, s83, 1
	s_cmp_ge_u32 s5, s42
	s_mov_b64 s[0:1], -1
	s_mul_i32 s86, s84, s42
	s_cbranch_scc0 .LBB0_378
	s_sub_i32 s0, s5, s42
	s_mul_i32 s0, s0, s83
	s_add_i32 s6, s0, s86
	s_mov_b64 s[0:1], 0

;     __device__ __forceinline__ void init(const int* cnt_, const void* A_, const void* B_, int N, int K, int rowmajor_, int maxT) {
;         rowmajor = rowmajor_;
;         cnt = cnt_; nN = N / BM; A = (const char*)A_; B = (const char*)B_; tstep = (size_t)BM * K * 2; estride = (size_t)N * K * 2;
;         int t = 0;
; #pragma unroll
;         for (int e = 0; e < NEXP; ++e) { tl[e] = __builtin_amdgcn_readfirstlane((cnt[e * CSTR] + 255) >> 8); t += tl[e]; }
;         T = t < maxT ? t : maxT;
;     }
.LBB0_399:
	s_andn2_b64 vcc, exec, s[0:1]
	s_cbranch_vccnz .LBB0_561
	v_readlane_b32 s0, v252, 30
	v_readlane_b32 s1, v252, 31
	v_readlane_b32 s4, v253, 50
	s_mov_b32 s3, s1
	s_lshl_b32 s2, s4, 9
	v_writelane_b32 v252, s0, 30
	v_mov_b32_e32 v2, v196
	s_mov_b32 s6, s74
	v_writelane_b32 v252, s1, 31
	s_lshl_b64 s[0:1], s[2:3], 2
	s_add_u32 s0, s28, s0
	s_addc_u32 s1, s29, s1
	global_load_dword v238, v1, s[0:1]
	global_load_dword v239, v1, s[0:1] offset:256
	global_load_dword v240, v1, s[0:1] offset:512
	global_load_dword v241, v1, s[0:1] offset:768
	global_load_dword v242, v1, s[0:1] offset:1024
	global_load_dword v243, v1, s[0:1] offset:1280
	global_load_dword v244, v1, s[0:1] offset:1536
	global_load_dword v245, v1, s[0:1] offset:1792
	s_waitcnt vmcnt(0)
	v_mov_b32_e32 v0, v238
	s_mul_i32 s2, s4, 0x7000000
	v_readlane_b32 s4, v250, 11
	s_add_u32 s36, s4, s2
	v_readlane_b32 s5, v250, 12
	s_addc_u32 s37, s5, 0
	s_waitcnt vmcnt(0)
	v_readfirstlane_b32 s2, v0
	v_mov_b32_e32 v0, v239
	s_addk_i32 s2, 0xff
	s_ashr_i32 s38, s2, 8
	s_mul_i32 s73, s38, 28
	s_waitcnt vmcnt(0)
	v_readfirstlane_b32 s2, v0
	v_mov_b32_e32 v0, v240
	s_addk_i32 s2, 0xff
	s_ashr_i32 s61, s2, 8
	s_add_i32 s52, s61, s38
	s_mul_i32 s40, s52, 28
	s_waitcnt vmcnt(0)
	v_readfirstlane_b32 s2, v0
	v_mov_b32_e32 v0, v241
	s_addk_i32 s2, 0xff
	s_ashr_i32 s83, s2, 8
	s_add_i32 s53, s83, s52
	s_mul_i32 s42, s53, 28
	s_waitcnt vmcnt(0)
	v_readfirstlane_b32 s2, v0
	v_mov_b32_e32 v0, v242
	s_addk_i32 s2, 0xff
	s_ashr_i32 s84, s2, 8
	s_add_i32 s72, s84, s53
	s_mul_i32 s46, s72, 28
	s_waitcnt vmcnt(0)
	v_readfirstlane_b32 s2, v0
	v_mov_b32_e32 v0, v243
	s_addk_i32 s2, 0xff
	s_ashr_i32 s85, s2, 8
	s_add_i32 s63, s85, s72
	s_mul_i32 s48, s63, 28
	s_waitcnt vmcnt(0)
	v_readfirstlane_b32 s2, v0
	v_mov_b32_e32 v0, v244
	s_addk_i32 s2, 0xff
	s_ashr_i32 s86, s2, 8
	s_add_i32 s30, s86, s63
	s_mul_i32 s60, s30, 28
	s_waitcnt vmcnt(0)
	v_readfirstlane_b32 s2, v0
	v_mov_b32_e32 v0, v245
	s_addk_i32 s2, 0xff
	s_ashr_i32 s87, s2, 8
	s_add_i32 s76, s87, s30
	s_waitcnt lgkmcnt(0)
	s_load_dword s79, s[50:51], 0x0
	v_readfirstlane_b32 s88, v2
	s_mul_i32 s70, s76, 28
	s_waitcnt vmcnt(0)
	v_readfirstlane_b32 s0, v0
	s_addk_i32 s0, 0xff
	s_ashr_i32 s77, s0, 8
	s_add_i32 s71, s77, s76
	s_min_i32 s78, s71, 0x100000
	s_mul_i32 s78, s78, 28
	s_cmp_lt_i32 s6, s78
	s_cselect_b64 s[0:1], -1, 0
	s_cmp_ge_i32 s6, s78
	s_mul_i32 s71, s71, 28
	s_cbranch_scc1 .LBB0_425
	s_ashr_i32 s10, s78, 3
	s_and_b32 s11, s78, 4
	s_and_b32 s7, s6, 7
	s_add_i32 s8, s10, 1
	s_cmp_ge_u32 s7, s11
	s_mov_b64 s[4:5], -1
	s_cbranch_scc0 .LBB0_403
	s_sub_i32 s3, s7, s11
	s_mul_i32 s2, s8, s11
	s_mul_i32 s3, s3, s10
	s_add_i32 s9, s3, s2
	s_mov_b64 s[4:5], 0

; __device__ __forceinline__ int get_tid() { int t = threadIdx.x; asm volatile("" : "+v"(t)); return t; }
; template <class Epi, class Sched>
; __device__ __forceinline__ void gemm_phase(LAS unsigned char* lds, const int K, const int lda, const int ldb, const Sched& S, const Epi& E) {
;     ...
;     auto mk_off = [&](const int (&ix)[2][2], unsigned (&vo)[2][2]) {
; #pragma unroll
;         for (int i = 0; i < 2; ++i) { int R, C; stage_rc(get_tid() * 16 + i * 8192, R, C);
; #pragma unroll
;             for (int h = 0; h < 2; ++h) vo[h][i] = (unsigned)ix[h][i] * (unsigned)(lda * 2) + (unsigned)C * 2u; } };
;     ...
;         const bool has_next = S.next(ui + 1, nxt);
;         const char* nA = has_next ? nxt.a : cA; const char* nB = has_next ? nxt.b : cB;
;         if constexpr (GATHER) {
;             nA = cA;
;             if (has_next) mk_off(ix1, vnxt);
;             else {
; #pragma unroll
;                 for (int h = 0; h < 2; ++h)
; #pragma unroll
;                     for (int i = 0; i < 2; ++i) vnxt[h][i] = vcur[h][i];
;             }
.LBB0_481:
	v_cndmask_b32_e64 v130, 0, 1, s[14:15]
	v_cmp_ne_u32_e64 s[0:1], 1, v130
	s_andn2_b64 vcc, exec, s[14:15]
	v_mov_b32_e32 v224, v178
	v_mov_b32_e32 v225, v180
	v_mov_b32_e32 v188, v0
	v_mov_b32_e32 v190, v182
	s_cbranch_vccnz .LBB0_483
	v_mov_b32_e32 v130, v196
	s_nop 0
	v_ashrrev_i32_e32 v132, 31, v130
	v_lshrrev_b32_e32 v132, 26, v132
	v_lshlrev_b32_e32 v131, 4, v130
	v_add_u32_e32 v132, v130, v132
	v_bfe_i32 v130, v130, 27, 1
	v_lshrrev_b32_e32 v130, 22, v130
	v_add_u32_e32 v130, v131, v130
	v_and_b32_e32 v130, 0xfffffc00, v130
	v_sub_u32_e32 v130, v131, v130
	v_lshrrev_b32_e32 v131, 4, v130
	v_bitop3_b32 v131, v131, v130, 32 bitop3:0x6c
	v_ashrrev_i32_e32 v130, 31, v130
	v_lshrrev_b32_e32 v130, 26, v130
	v_add_u32_e32 v130, v131, v130
	v_and_b32_e32 v130, 0xc0, v130
	v_sub_u32_e32 v130, v131, v130
	v_lshrrev_b32_e32 v132, 1, v132
	v_ashrrev_i16_sdwa v130, v200, sext(v130) dst_sel:DWORD dst_unused:UNUSED_PAD src0_sel:DWORD src1_sel:BYTE_0
	v_and_b32_e32 v132, 32, v132
	v_bfe_i32 v130, v130, 0, 16
	v_add_lshl_u32 v130, v132, v130, 1
	s_waitcnt vmcnt(8)
	v_lshl_add_u32 v224, v216, 11, v130
	v_lshl_add_u32 v188, v217, 11, v130
	v_mov_b32_e32 v130, v196
	s_nop 0
	v_lshl_add_u32 v130, v130, 4, v210
	v_ashrrev_i32_e32 v131, 31, v130
	v_lshrrev_b32_e32 v131, 22, v131
	v_add_u32_e32 v131, v130, v131
	v_ashrrev_i32_e32 v131, 10, v131
	v_mul_i32_i24_e32 v132, 0x400, v131
	v_sub_u32_e32 v130, v130, v132
	v_lshrrev_b32_e32 v132, 4, v130
	v_bitop3_b32 v132, v132, v130, 32 bitop3:0x6c
	v_ashrrev_i32_e32 v130, 31, v130
	v_lshrrev_b32_e32 v130, 26, v130
	v_add_u32_e32 v130, v132, v130
	v_and_b32_e32 v130, 0xc0, v130
	v_sub_u32_e32 v130, v132, v130
	v_lshlrev_b32_e32 v131, 5, v131
	v_ashrrev_i16_sdwa v130, v200, sext(v130) dst_sel:DWORD dst_unused:UNUSED_PAD src0_sel:DWORD src1_sel:BYTE_0
	v_and_b32_e32 v131, 32, v131
	v_bfe_i32 v130, v130, 0, 16
	v_add_lshl_u32 v130, v131, v130, 1
	v_lshl_add_u32 v225, v218, 11, v130
	v_lshl_add_u32 v190, v219, 11, v130
